# grid-sync poll loop issues its coherent loads back to back (the s_sleep between polls replaced by s_nop)
# baseline (speedup 1.0000x reference)
; __global__ void __launch_bounds__(512) hybrid_layer_megakernel(Params p, int ph_lo, int ph_hi) {
;     ...
;     if (ph < ph_hi) { cg::this_grid().sync(); }
.LBB0_2208:
	s_nop 0
	global_load_dword v1, v177, s[4:5] offset:32 sc1
	s_waitcnt vmcnt(0)
	v_and_b32_e32 v1, 0xffff0000, v1
	v_cmp_ne_u32_e32 vcc, v1, v0
	s_or_b64 s[6:7], vcc, s[6:7]
	s_andn2_b64 exec, exec, s[6:7]
	s_cbranch_execnz .LBB0_2208
	s_getpc_b64 s[98:99]
